# grid barrier leader: acquire-invalidate issued before the cross-XCD arrival, per-XCD generation bump removed
# baseline (speedup 1.0000x reference)
.LBB0_10:
	s_or_b64 exec, exec, s[26:27]
	s_waitcnt vmcnt(0)

.LBB0_1221:
	s_mov_b64 s[26:27], exec
	buffer_wbl2 sc1
	s_waitcnt lgkmcnt(0)
	s_waitcnt vmcnt(0)
	buffer_inv sc1
	v_mbcnt_lo_u32_b32 v1, s26, 0
	v_mbcnt_hi_u32_b32 v1, s27, v1
	v_cmp_eq_u32_e32 vcc, 0, v1
	s_and_saveexec_b64 s[34:35], vcc
	s_cbranch_execz .LBB0_1223
	s_bcnt1_i32_b64 s0, s[26:27]
	v_readlane_b32 s2, v254, 7
	v_mov_b32_e32 v2, s0
	v_readlane_b32 s3, v254, 8
	s_nop 4
	global_atomic_add v2, v33, v2, s[2:3] sc0
